# FoX loop unrolled x2 with alternating S buffers (no register copy)
# speedup vs baseline: 1.0164x; 1.0027x over previous
.Lff1a_copy:
	s_nop 7
	s_cbranch_vccz .Lff1a_norsc
	v_max_f32_e32 v0, v0, v0
	v_max_f32_e32 v251, v197, v197
	v_max_f32_e32 v251, v251, v0
	v_sub_f32_e32 v252, v197, v251
	v_exp_f32_e32 v252, v252
	v_mov_b32_e32 v197, v251
	s_nop 0
	v_mul_f32_e32 v196, v196, v252
	s_nop 1
	v_pk_mul_f32 v[64:65], v[64:65], v[252:253] op_sel_hi:[1,0]
	v_pk_mul_f32 v[62:63], v[62:63], v[252:253] op_sel_hi:[1,0]
	v_pk_mul_f32 v[60:61], v[60:61], v[252:253] op_sel_hi:[1,0]
	v_pk_mul_f32 v[58:59], v[58:59], v[252:253] op_sel_hi:[1,0]
	v_pk_mul_f32 v[56:57], v[56:57], v[252:253] op_sel_hi:[1,0]
	v_pk_mul_f32 v[54:55], v[54:55], v[252:253] op_sel_hi:[1,0]
	v_pk_mul_f32 v[52:53], v[52:53], v[252:253] op_sel_hi:[1,0]
	v_pk_mul_f32 v[50:51], v[50:51], v[252:253] op_sel_hi:[1,0]
	v_pk_mul_f32 v[48:49], v[48:49], v[252:253] op_sel_hi:[1,0]
	v_pk_mul_f32 v[46:47], v[46:47], v[252:253] op_sel_hi:[1,0]
	v_pk_mul_f32 v[44:45], v[44:45], v[252:253] op_sel_hi:[1,0]
	v_pk_mul_f32 v[42:43], v[42:43], v[252:253] op_sel_hi:[1,0]
	v_pk_mul_f32 v[40:41], v[40:41], v[252:253] op_sel_hi:[1,0]
	v_pk_mul_f32 v[38:39], v[38:39], v[252:253] op_sel_hi:[1,0]
	v_pk_mul_f32 v[36:37], v[36:37], v[252:253] op_sel_hi:[1,0]
	v_pk_mul_f32 v[34:35], v[34:35], v[252:253] op_sel_hi:[1,0]
	v_pk_mul_f32 v[32:33], v[32:33], v[252:253] op_sel_hi:[1,0]
	v_pk_mul_f32 v[30:31], v[30:31], v[252:253] op_sel_hi:[1,0]
	v_pk_mul_f32 v[28:29], v[28:29], v[252:253] op_sel_hi:[1,0]
	v_pk_mul_f32 v[26:27], v[26:27], v[252:253] op_sel_hi:[1,0]
	v_pk_mul_f32 v[24:25], v[24:25], v[252:253] op_sel_hi:[1,0]
	v_pk_mul_f32 v[22:23], v[22:23], v[252:253] op_sel_hi:[1,0]
	v_pk_mul_f32 v[20:21], v[20:21], v[252:253] op_sel_hi:[1,0]
	v_pk_mul_f32 v[18:19], v[18:19], v[252:253] op_sel_hi:[1,0]
	v_pk_mul_f32 v[16:17], v[16:17], v[252:253] op_sel_hi:[1,0]
	v_pk_mul_f32 v[14:15], v[14:15], v[252:253] op_sel_hi:[1,0]
	v_pk_mul_f32 v[12:13], v[12:13], v[252:253] op_sel_hi:[1,0]
	v_pk_mul_f32 v[10:11], v[10:11], v[252:253] op_sel_hi:[1,0]
	v_pk_mul_f32 v[8:9], v[8:9], v[252:253] op_sel_hi:[1,0]
	v_pk_mul_f32 v[6:7], v[6:7], v[252:253] op_sel_hi:[1,0]
	v_pk_mul_f32 v[4:5], v[4:5], v[252:253] op_sel_hi:[1,0]
	v_pk_mul_f32 v[2:3], v[2:3], v[252:253] op_sel_hi:[1,0]

.Lff1a_exit:
	s_cmp_eq_u32 s72, 0
	s_cbranch_scc1 .Lff1a_done
	v_sub_f32_e32 v218, v218, v197
	v_sub_f32_e32 v219, v219, v197
	v_sub_f32_e32 v220, v220, v197
	v_sub_f32_e32 v221, v221, v197
	v_exp_f32_e32 v218, v218
	v_exp_f32_e32 v219, v219
	v_exp_f32_e32 v220, v220
	v_exp_f32_e32 v221, v221
	v_sub_f32_e32 v222, v222, v197
	v_sub_f32_e32 v223, v223, v197
	v_sub_f32_e32 v224, v224, v197
	v_sub_f32_e32 v225, v225, v197
	v_exp_f32_e32 v222, v222
	v_exp_f32_e32 v223, v223
	v_exp_f32_e32 v224, v224
	v_exp_f32_e32 v225, v225
	v_sub_f32_e32 v234, v234, v197
	v_sub_f32_e32 v235, v235, v197
	v_sub_f32_e32 v236, v236, v197
	v_sub_f32_e32 v237, v237, v197
	v_exp_f32_e32 v234, v234
	v_exp_f32_e32 v235, v235
	v_exp_f32_e32 v236, v236
	v_exp_f32_e32 v237, v237
	v_add_f32_e32 v250, v218, v222
	v_add_f32_e32 v251, v219, v223
	v_add_f32_e32 v252, v220, v224
	v_add_f32_e32 v253, v221, v225
	v_sub_f32_e32 v238, v238, v197
	v_sub_f32_e32 v239, v239, v197
	v_sub_f32_e32 v240, v240, v197
	v_sub_f32_e32 v241, v241, v197
	v_exp_f32_e32 v238, v238
	v_exp_f32_e32 v239, v239
	v_exp_f32_e32 v240, v240
	v_exp_f32_e32 v241, v241
	v_add_f32_e32 v250, v250, v234
	v_add_f32_e32 v251, v251, v235
	v_add_f32_e32 v252, v252, v236
	v_add_f32_e32 v253, v253, v237
	v_sub_f32_e32 v226, v226, v197
	v_sub_f32_e32 v227, v227, v197
	v_sub_f32_e32 v228, v228, v197
	v_sub_f32_e32 v229, v229, v197
	v_exp_f32_e32 v226, v226
	v_exp_f32_e32 v227, v227
	v_exp_f32_e32 v228, v228
	v_exp_f32_e32 v229, v229
	v_add_f32_e32 v250, v250, v238
	v_add_f32_e32 v251, v251, v239
	v_add_f32_e32 v252, v252, v240
	v_add_f32_e32 v253, v253, v241
	v_sub_f32_e32 v230, v230, v197
	v_sub_f32_e32 v231, v231, v197
	v_sub_f32_e32 v232, v232, v197
	v_sub_f32_e32 v233, v233, v197
	v_exp_f32_e32 v230, v230
	v_exp_f32_e32 v231, v231
	v_exp_f32_e32 v232, v232
	v_exp_f32_e32 v233, v233
	v_add_f32_e32 v250, v250, v226
	v_add_f32_e32 v251, v251, v227
	v_add_f32_e32 v252, v252, v228
	v_add_f32_e32 v253, v253, v229
	v_sub_f32_e32 v242, v242, v197
	v_sub_f32_e32 v243, v243, v197
	v_sub_f32_e32 v244, v244, v197
	v_sub_f32_e32 v245, v245, v197
	v_exp_f32_e32 v242, v242
	v_exp_f32_e32 v243, v243
	v_exp_f32_e32 v244, v244
	v_exp_f32_e32 v245, v245
	v_add_f32_e32 v250, v250, v230
	v_add_f32_e32 v251, v251, v231
	v_add_f32_e32 v252, v252, v232
	v_add_f32_e32 v253, v253, v233
	v_sub_f32_e32 v246, v246, v197
	v_sub_f32_e32 v247, v247, v197
	v_sub_f32_e32 v248, v248, v197
	v_sub_f32_e32 v249, v249, v197
	v_exp_f32_e32 v246, v246
	v_exp_f32_e32 v247, v247
	v_exp_f32_e32 v248, v248
	v_exp_f32_e32 v249, v249
	v_add_f32_e32 v250, v250, v242
	v_add_f32_e32 v251, v251, v243
	v_add_f32_e32 v252, v252, v244
	v_add_f32_e32 v253, v253, v245
	v_add_f32_e32 v250, v250, v246
	v_add_f32_e32 v251, v251, v247
	v_add_f32_e32 v252, v252, v248
	v_add_f32_e32 v253, v253, v249
	v_add_f32_e32 v250, v250, v251
	v_add_f32_e32 v252, v252, v253
	v_add_f32_e32 v250, v250, v252
	v_add_f32_e32 v196, v196, v250
	v_cvt_pk_bf16_f32 v241, v240, v241
	v_cvt_pk_bf16_f32 v240, v238, v239
	v_cvt_pk_bf16_f32 v239, v236, v237
	v_cvt_pk_bf16_f32 v238, v234, v235
	v_cvt_pk_bf16_f32 v234, v218, v219
	v_cvt_pk_bf16_f32 v235, v220, v221
	v_cvt_pk_bf16_f32 v236, v222, v223
	v_cvt_pk_bf16_f32 v237, v224, v225
	v_cvt_pk_bf16_f32 v249, v248, v249
	v_cvt_pk_bf16_f32 v248, v246, v247
	v_cvt_pk_bf16_f32 v247, v244, v245
	v_cvt_pk_bf16_f32 v246, v242, v243
	v_cvt_pk_bf16_f32 v242, v226, v227
	v_cvt_pk_bf16_f32 v243, v228, v229
	v_cvt_pk_bf16_f32 v244, v230, v231
	v_cvt_pk_bf16_f32 v245, v232, v233
	v_add_u32_e32 v250, s70, v164
	ds_read_b64_tr_b16 v[218:219], v250 offset:34816
	ds_read_b64_tr_b16 v[220:221], v250 offset:37376
	ds_read_b64_tr_b16 v[222:223], v250 offset:39936
	ds_read_b64_tr_b16 v[224:225], v250 offset:42496
	ds_read_b64_tr_b16 v[226:227], v250 offset:45056
	ds_read_b64_tr_b16 v[228:229], v250 offset:47616
	ds_read_b64_tr_b16 v[230:231], v250 offset:50176
	ds_read_b64_tr_b16 v[232:233], v250 offset:52736
	s_waitcnt lgkmcnt(6)
	v_mfma_f32_32x32x16_bf16 v[50:65], v[218:221], v[234:237], v[50:65]
	s_waitcnt lgkmcnt(4)
	v_mfma_f32_32x32x16_bf16 v[50:65], v[222:225], v[242:245], v[50:65]
	s_waitcnt lgkmcnt(2)
	v_mfma_f32_32x32x16_bf16 v[50:65], v[226:229], v[238:241], v[50:65]
	ds_read_b64_tr_b16 v[218:219], v250 offset:34880
	ds_read_b64_tr_b16 v[220:221], v250 offset:37440
	ds_read_b64_tr_b16 v[222:223], v250 offset:40000
	ds_read_b64_tr_b16 v[224:225], v250 offset:42560
	ds_read_b64_tr_b16 v[226:227], v250 offset:45120
	ds_read_b64_tr_b16 v[228:229], v250 offset:47680
	ds_read_b64_tr_b16 v[198:199], v250 offset:50240
	ds_read_b64_tr_b16 v[200:201], v250 offset:52800
	s_waitcnt lgkmcnt(8)
	v_mfma_f32_32x32x16_bf16 v[50:65], v[230:233], v[246:249], v[50:65]
	s_waitcnt lgkmcnt(6)
	v_mfma_f32_32x32x16_bf16 v[34:49], v[218:221], v[234:237], v[34:49]
	s_waitcnt lgkmcnt(4)
	v_mfma_f32_32x32x16_bf16 v[34:49], v[222:225], v[242:245], v[34:49]
	s_waitcnt lgkmcnt(2)
	v_mfma_f32_32x32x16_bf16 v[34:49], v[226:229], v[238:241], v[34:49]
	ds_read_b64_tr_b16 v[218:219], v250 offset:34944
	ds_read_b64_tr_b16 v[220:221], v250 offset:37504
	ds_read_b64_tr_b16 v[222:223], v250 offset:40064
	ds_read_b64_tr_b16 v[224:225], v250 offset:42624
	ds_read_b64_tr_b16 v[226:227], v250 offset:45184
	ds_read_b64_tr_b16 v[228:229], v250 offset:47744
	ds_read_b64_tr_b16 v[230:231], v250 offset:50304
	ds_read_b64_tr_b16 v[232:233], v250 offset:52864
	s_waitcnt lgkmcnt(8)
	v_mfma_f32_32x32x16_bf16 v[34:49], v[198:201], v[246:249], v[34:49]
	s_waitcnt lgkmcnt(6)
	v_mfma_f32_32x32x16_bf16 v[18:33], v[218:221], v[234:237], v[18:33]
	s_waitcnt lgkmcnt(4)
	v_mfma_f32_32x32x16_bf16 v[18:33], v[222:225], v[242:245], v[18:33]
	s_waitcnt lgkmcnt(2)
	v_mfma_f32_32x32x16_bf16 v[18:33], v[226:229], v[238:241], v[18:33]
	ds_read_b64_tr_b16 v[218:219], v250 offset:35008
	ds_read_b64_tr_b16 v[220:221], v250 offset:37568
	ds_read_b64_tr_b16 v[222:223], v250 offset:40128
	ds_read_b64_tr_b16 v[224:225], v250 offset:42688
	ds_read_b64_tr_b16 v[226:227], v250 offset:45248
	ds_read_b64_tr_b16 v[228:229], v250 offset:47808
	ds_read_b64_tr_b16 v[198:199], v250 offset:50368
	ds_read_b64_tr_b16 v[200:201], v250 offset:52928
	s_waitcnt lgkmcnt(8)
	v_mfma_f32_32x32x16_bf16 v[18:33], v[230:233], v[246:249], v[18:33]
	s_waitcnt lgkmcnt(6)
	v_mfma_f32_32x32x16_bf16 v[2:17], v[218:221], v[234:237], v[2:17]
	s_waitcnt lgkmcnt(4)
	v_mfma_f32_32x32x16_bf16 v[2:17], v[222:225], v[242:245], v[2:17]
	s_waitcnt lgkmcnt(2)
	v_mfma_f32_32x32x16_bf16 v[2:17], v[226:229], v[238:241], v[2:17]
	s_waitcnt lgkmcnt(0)
	v_mfma_f32_32x32x16_bf16 v[2:17], v[198:201], v[246:249], v[2:17]

.Lff1b_top:
	s_add_i32 s27, s0, -2
	s_and_b32 s27, s27, 1
	s_xor_b32 s34, s27, 1
	s_mul_i32 s35, s34, 0x4400
	s_add_i32 s35, s35, 0
	s_mulk_i32 s34, 0xc00
	s_add_i32 s34, s35, s34
	v_add3_u32 v0, s35, v157, v158
	s_waitcnt vmcnt(3)
	ds_write_b128 v0, v[130:133]
	v_add3_u32 v0, s68, v159, v158
	s_waitcnt vmcnt(2)
	ds_write_b128 v0, v[134:137] offset:34816
	v_add3_u32 v0, s35, v160, v161
	s_cmp_lt_u32 s0, s1
	s_waitcnt vmcnt(1)
	ds_write_b128 v0, v[138:141]
	v_add3_u32 v0, s68, v147, v161
	s_cselect_b32 s34, s0, s6
	s_lshl_b32 s34, s34, 6
	v_add_u32_e32 v250, s34, v146
	v_ashrrev_i32_e32 v251, 31, v250
	v_lshlrev_b64 v[250:251], 14, v[250:251]
	v_lshl_add_u64 v[250:251], v[150:151], 0, v[250:251]
	v_add_co_u32_e32 v252, vcc, s42, v250
	s_waitcnt vmcnt(0)
	ds_write_b128 v0, v[142:145] offset:34816
	v_addc_co_u32_e32 v253, vcc, 0, v251, vcc
	v_add_co_u32_e32 v250, vcc, 0x2000, v250
	s_nop 1
	v_addc_co_u32_e32 v251, vcc, 0, v251, vcc
	global_load_dwordx4 v[130:133], v[252:253], off
	global_load_dwordx4 v[134:137], v[250:251], off
	v_add_u32_e32 v250, s34, v148
	v_ashrrev_i32_e32 v251, 31, v250
	v_lshlrev_b64 v[250:251], 14, v[250:251]
	v_lshl_add_u64 v[250:251], v[152:153], 0, v[250:251]
	v_add_co_u32_e32 v252, vcc, 0x1000, v250
	s_sub_i32 s34, s26, 63
	s_nop 0
	v_addc_co_u32_e32 v253, vcc, 0, v251, vcc
	v_add_co_u32_e32 v250, vcc, 0x2000, v250
	s_cmp_gt_i32 s34, s5
	s_nop 0
	v_addc_co_u32_e32 v251, vcc, 0, v251, vcc
	global_load_dwordx4 v[138:141], v[252:253], off
	global_load_dwordx4 v[142:145], v[250:251], off
	s_sub_i32 s34, s26, 63
	s_cmp_gt_i32 s34, s5
	s_cbranch_scc1 .Lff1b_inact
	s_cmp_eq_u32 s72, 0
	s_cbranch_scc1 .Lff1b_first
	s_mul_i32 s34, s27, 0x4400
	v_add_u32_e32 v0, s34, v162
	ds_read_b128 v[198:201], v0
	ds_read_b128 v[202:205], v0 offset:32
	ds_read_b128 v[206:209], v0 offset:8704
	ds_read_b128 v[210:213], v0 offset:8736
	v_add_u32_e32 v78, s4, v149
	v_add_u32_e32 v66, 0x12800, v78
	v_add_u32_e32 v67, 0x12880, v78
	v_add_u32_e32 v70, 0x12820, v78
	v_add_u32_e32 v71, 0x128a0, v78
	v_add_u32_e32 v74, 0x12840, v78
	v_add_u32_e32 v75, 0x128c0, v78
	v_add_u32_e32 v79, 0x12860, v78
	v_add_u32_e32 v78, 0x128e0, v78
	ds_read_b128 v[82:85], v66
	ds_read_b128 v[66:69], v67
	ds_read_b128 v[86:89], v70
	ds_read_b128 v[70:73], v71
	ds_read_b128 v[90:93], v74
	ds_read_b128 v[74:77], v75
	ds_read_b128 v[94:97], v79
	ds_read_b128 v[78:81], v78
	s_waitcnt lgkmcnt(1)
	v_mfma_f32_32x32x16_bf16 v[82:97], v[198:201], v[98:101], v[82:97]
	v_sub_f32_e32 v218, v218, v197
	v_sub_f32_e32 v219, v219, v197
	v_sub_f32_e32 v220, v220, v197
	v_sub_f32_e32 v221, v221, v197
	v_exp_f32_e32 v218, v218
	v_exp_f32_e32 v219, v219
	v_exp_f32_e32 v220, v220
	v_exp_f32_e32 v221, v221
	s_waitcnt lgkmcnt(0)
	v_mfma_f32_32x32x16_bf16 v[66:81], v[206:209], v[98:101], v[66:81]
	v_sub_f32_e32 v222, v222, v197
	v_sub_f32_e32 v223, v223, v197
	v_sub_f32_e32 v224, v224, v197
	v_sub_f32_e32 v225, v225, v197
	v_exp_f32_e32 v222, v222
	v_exp_f32_e32 v223, v223
	v_exp_f32_e32 v224, v224
	v_exp_f32_e32 v225, v225
	v_mfma_f32_32x32x16_bf16 v[82:97], v[202:205], v[102:105], v[82:97]
	v_sub_f32_e32 v234, v234, v197
	v_sub_f32_e32 v235, v235, v197
	v_sub_f32_e32 v236, v236, v197
	v_sub_f32_e32 v237, v237, v197
	v_exp_f32_e32 v234, v234
	v_exp_f32_e32 v235, v235
	v_exp_f32_e32 v236, v236
	v_exp_f32_e32 v237, v237
	ds_read_b128 v[198:201], v0 offset:64
	ds_read_b128 v[202:205], v0 offset:96
	ds_read_b128 v[206:209], v0 offset:8768
	ds_read_b128 v[214:217], v0 offset:8800
	v_mfma_f32_32x32x16_bf16 v[66:81], v[210:213], v[102:105], v[66:81]
	v_add_f32_e32 v250, v218, v222
	v_add_f32_e32 v251, v219, v223
	v_add_f32_e32 v252, v220, v224
	v_add_f32_e32 v253, v221, v225
	v_sub_f32_e32 v238, v238, v197
	v_sub_f32_e32 v239, v239, v197
	v_sub_f32_e32 v240, v240, v197
	v_sub_f32_e32 v241, v241, v197
	s_waitcnt lgkmcnt(3)
	v_mfma_f32_32x32x16_bf16 v[82:97], v[198:201], v[106:109], v[82:97]
	v_exp_f32_e32 v238, v238
	v_exp_f32_e32 v239, v239
	v_exp_f32_e32 v240, v240
	v_exp_f32_e32 v241, v241
	v_add_f32_e32 v250, v250, v234
	v_add_f32_e32 v251, v251, v235
	v_add_f32_e32 v252, v252, v236
	v_add_f32_e32 v253, v253, v237
	s_waitcnt lgkmcnt(1)
	v_mfma_f32_32x32x16_bf16 v[66:81], v[206:209], v[106:109], v[66:81]
	v_sub_f32_e32 v226, v226, v197
	v_sub_f32_e32 v227, v227, v197
	v_sub_f32_e32 v228, v228, v197
	v_sub_f32_e32 v229, v229, v197
	v_exp_f32_e32 v226, v226
	v_exp_f32_e32 v227, v227
	v_exp_f32_e32 v228, v228
	v_exp_f32_e32 v229, v229
	v_mfma_f32_32x32x16_bf16 v[82:97], v[202:205], v[110:113], v[82:97]
	v_add_f32_e32 v250, v250, v238
	v_add_f32_e32 v251, v251, v239
	v_add_f32_e32 v252, v252, v240
	v_add_f32_e32 v253, v253, v241
	v_sub_f32_e32 v230, v230, v197
	v_sub_f32_e32 v231, v231, v197
	v_sub_f32_e32 v232, v232, v197
	v_sub_f32_e32 v233, v233, v197
	ds_read_b128 v[198:201], v0 offset:128
	ds_read_b128 v[202:205], v0 offset:160
	ds_read_b128 v[206:209], v0 offset:8832
	ds_read_b128 v[210:213], v0 offset:8864
	s_waitcnt lgkmcnt(4)
	v_mfma_f32_32x32x16_bf16 v[66:81], v[214:217], v[110:113], v[66:81]
	v_exp_f32_e32 v230, v230
	v_exp_f32_e32 v231, v231
	v_exp_f32_e32 v232, v232
	v_exp_f32_e32 v233, v233
	v_add_f32_e32 v250, v250, v226
	v_add_f32_e32 v251, v251, v227
	v_add_f32_e32 v252, v252, v228
	v_add_f32_e32 v253, v253, v229
	s_waitcnt lgkmcnt(3)
	v_mfma_f32_32x32x16_bf16 v[82:97], v[198:201], v[114:117], v[82:97]
	v_sub_f32_e32 v242, v242, v197
	v_sub_f32_e32 v243, v243, v197
	v_sub_f32_e32 v244, v244, v197
	v_sub_f32_e32 v245, v245, v197
	v_exp_f32_e32 v242, v242
	v_exp_f32_e32 v243, v243
	v_exp_f32_e32 v244, v244
	v_exp_f32_e32 v245, v245
	s_waitcnt lgkmcnt(1)
	v_mfma_f32_32x32x16_bf16 v[66:81], v[206:209], v[114:117], v[66:81]
	v_add_f32_e32 v250, v250, v230
	v_add_f32_e32 v251, v251, v231
	v_add_f32_e32 v252, v252, v232
	v_add_f32_e32 v253, v253, v233
	v_sub_f32_e32 v246, v246, v197
	v_sub_f32_e32 v247, v247, v197
	v_sub_f32_e32 v248, v248, v197
	v_sub_f32_e32 v249, v249, v197
	v_mfma_f32_32x32x16_bf16 v[82:97], v[202:205], v[118:121], v[82:97]
	v_exp_f32_e32 v246, v246
	v_exp_f32_e32 v247, v247
	v_exp_f32_e32 v248, v248
	v_exp_f32_e32 v249, v249
	v_add_f32_e32 v250, v250, v242
	v_add_f32_e32 v251, v251, v243
	v_add_f32_e32 v252, v252, v244
	v_add_f32_e32 v253, v253, v245
	ds_read_b128 v[198:201], v0 offset:192
	ds_read_b128 v[202:205], v0 offset:224
	ds_read_b128 v[206:209], v0 offset:8896
	ds_read_b128 v[214:217], v0 offset:8928
	s_waitcnt lgkmcnt(4)
	v_mfma_f32_32x32x16_bf16 v[66:81], v[210:213], v[118:121], v[66:81]
	v_add_f32_e32 v250, v250, v246
	v_add_f32_e32 v251, v251, v247
	v_add_f32_e32 v252, v252, v248
	v_add_f32_e32 v253, v253, v249
	v_add_f32_e32 v250, v250, v251
	v_add_f32_e32 v252, v252, v253
	v_add_f32_e32 v250, v250, v252
	v_add_f32_e32 v196, v196, v250
	s_waitcnt lgkmcnt(3)
	v_mfma_f32_32x32x16_bf16 v[82:97], v[198:201], v[122:125], v[82:97]
	v_cvt_pk_bf16_f32 v241, v240, v241
	v_cvt_pk_bf16_f32 v240, v238, v239
	v_cvt_pk_bf16_f32 v239, v236, v237
	v_cvt_pk_bf16_f32 v238, v234, v235
	v_cvt_pk_bf16_f32 v234, v218, v219
	v_cvt_pk_bf16_f32 v235, v220, v221
	v_cvt_pk_bf16_f32 v236, v222, v223
	v_cvt_pk_bf16_f32 v237, v224, v225
	s_waitcnt lgkmcnt(1)
	v_mfma_f32_32x32x16_bf16 v[66:81], v[206:209], v[122:125], v[66:81]
	v_cvt_pk_bf16_f32 v249, v248, v249
	v_cvt_pk_bf16_f32 v248, v246, v247
	v_cvt_pk_bf16_f32 v247, v244, v245
	v_cvt_pk_bf16_f32 v246, v242, v243
	v_cvt_pk_bf16_f32 v242, v226, v227
	v_cvt_pk_bf16_f32 v243, v228, v229
	v_cvt_pk_bf16_f32 v244, v230, v231
	v_cvt_pk_bf16_f32 v245, v232, v233
	v_mfma_f32_32x32x16_bf16 v[82:97], v[202:205], v[126:129], v[82:97]
	s_waitcnt lgkmcnt(0)
	v_mfma_f32_32x32x16_bf16 v[66:81], v[214:217], v[126:129], v[66:81]
	s_cmp_le_i32 s26, s5
	s_cbranch_scc1 .Lff1b_z2
	v_cmp_le_i32_e32 vcc, v165, v195
	s_nop 8
	v_cndmask_b32_e32 v66, v155, v66, vcc
	v_cmp_lt_i32_e32 vcc, v163, v195
	s_nop 1
	v_cndmask_b32_e32 v83, v155, v83, vcc
	v_cmp_le_i32_e32 vcc, v163, v195
	s_nop 1
	v_cndmask_b32_e32 v82, v155, v82, vcc
	v_cmp_le_i32_e32 vcc, v166, v195
	s_nop 1
	v_cndmask_b32_e32 v67, v155, v67, vcc
	v_cmp_le_i32_e32 vcc, v167, v195
	s_nop 1
	v_cndmask_b32_e32 v84, v155, v84, vcc
	v_cmp_le_i32_e32 vcc, v168, v195
	s_nop 1
	v_cndmask_b32_e32 v68, v155, v68, vcc
	v_cmp_le_i32_e32 vcc, v169, v195
	s_nop 1
	v_cndmask_b32_e32 v85, v155, v85, vcc
	v_cmp_le_i32_e32 vcc, v170, v195
	s_nop 1
	v_cndmask_b32_e32 v69, v155, v69, vcc
	v_cmp_le_i32_e32 vcc, v171, v195
	s_nop 1
	v_cndmask_b32_e32 v86, v155, v86, vcc
	v_cmp_le_i32_e32 vcc, v172, v195
	s_nop 1
	v_cndmask_b32_e32 v70, v155, v70, vcc
	v_cmp_le_i32_e32 vcc, v173, v195
	s_nop 1
	v_cndmask_b32_e32 v87, v155, v87, vcc
	v_cmp_le_i32_e32 vcc, v174, v195
	s_nop 1
	v_cndmask_b32_e32 v71, v155, v71, vcc
	v_cmp_le_i32_e32 vcc, v175, v195
	s_nop 1
	v_cndmask_b32_e32 v88, v155, v88, vcc
	v_cmp_le_i32_e32 vcc, v176, v195
	s_nop 1
	v_cndmask_b32_e32 v72, v155, v72, vcc
	v_cmp_le_i32_e32 vcc, v177, v195
	s_nop 1
	v_cndmask_b32_e32 v89, v155, v89, vcc
	v_cmp_le_i32_e32 vcc, v178, v195
	s_nop 1
	v_cndmask_b32_e32 v73, v155, v73, vcc
	v_cmp_le_i32_e32 vcc, v179, v195
	s_nop 1
	v_cndmask_b32_e32 v90, v155, v90, vcc
	v_cmp_le_i32_e32 vcc, v180, v195
	s_nop 1
	v_cndmask_b32_e32 v74, v155, v74, vcc
	v_cmp_le_i32_e32 vcc, v181, v195
	s_nop 1
	v_cndmask_b32_e32 v91, v155, v91, vcc
	v_cmp_le_i32_e32 vcc, v182, v195
	s_nop 1
	v_cndmask_b32_e32 v75, v155, v75, vcc
	v_cmp_le_i32_e32 vcc, v183, v195
	s_nop 1
	v_cndmask_b32_e32 v92, v155, v92, vcc
	v_cmp_le_i32_e32 vcc, v184, v195
	s_nop 1
	v_cndmask_b32_e32 v76, v155, v76, vcc
	v_cmp_le_i32_e32 vcc, v185, v195
	s_nop 1
	v_cndmask_b32_e32 v93, v155, v93, vcc
	v_cmp_le_i32_e32 vcc, v186, v195
	s_nop 1
	v_cndmask_b32_e32 v77, v155, v77, vcc
	v_cmp_le_i32_e32 vcc, v187, v195
	s_nop 1
	v_cndmask_b32_e32 v94, v155, v94, vcc
	v_cmp_le_i32_e32 vcc, v188, v195
	s_nop 1
	v_cndmask_b32_e32 v78, v155, v78, vcc
	v_cmp_le_i32_e32 vcc, v189, v195
	s_nop 1
	v_cndmask_b32_e32 v95, v155, v95, vcc
	v_cmp_le_i32_e32 vcc, v190, v195
	s_nop 1
	v_cndmask_b32_e32 v79, v155, v79, vcc
	v_cmp_le_i32_e32 vcc, v191, v195
	s_nop 1
	v_cndmask_b32_e32 v96, v155, v96, vcc
	v_cmp_le_i32_e32 vcc, v192, v195
	s_nop 1
	v_cndmask_b32_e32 v80, v155, v80, vcc
	v_cmp_le_i32_e32 vcc, v193, v195
	s_nop 1
	v_cndmask_b32_e32 v97, v155, v97, vcc
	v_cmp_le_i32_e32 vcc, v194, v195
	s_nop 1
	v_cndmask_b32_e32 v81, v155, v81, vcc
.Lff1b_z2:
	v_add_u32_e32 v250, s70, v164
	ds_read_b64_tr_b16 v[218:219], v250 offset:34816
	ds_read_b64_tr_b16 v[220:221], v250 offset:37376
	ds_read_b64_tr_b16 v[222:223], v250 offset:39936
	ds_read_b64_tr_b16 v[224:225], v250 offset:42496
	ds_read_b64_tr_b16 v[226:227], v250 offset:45056
	ds_read_b64_tr_b16 v[228:229], v250 offset:47616
	ds_read_b64_tr_b16 v[230:231], v250 offset:50176
	ds_read_b64_tr_b16 v[232:233], v250 offset:52736
	s_waitcnt lgkmcnt(6)
	v_mfma_f32_32x32x16_bf16 v[50:65], v[218:221], v[234:237], v[50:65]
	s_waitcnt lgkmcnt(4)
	v_mfma_f32_32x32x16_bf16 v[50:65], v[222:225], v[242:245], v[50:65]
	v_max3_f32 v0, v82, v66, v83
	v_max3_f32 v251, v86, v70, v87
	v_max3_f32 v252, v90, v74, v91
	s_waitcnt lgkmcnt(2)
	v_mfma_f32_32x32x16_bf16 v[50:65], v[226:229], v[238:241], v[50:65]
	v_max3_f32 v253, v94, v78, v95
	v_max3_f32 v0, v0, v67, v84
	v_max3_f32 v251, v251, v71, v88
	ds_read_b64_tr_b16 v[218:219], v250 offset:34880
	ds_read_b64_tr_b16 v[220:221], v250 offset:37440
	ds_read_b64_tr_b16 v[222:223], v250 offset:40000
	ds_read_b64_tr_b16 v[224:225], v250 offset:42560
	ds_read_b64_tr_b16 v[226:227], v250 offset:45120
	ds_read_b64_tr_b16 v[228:229], v250 offset:47680
	ds_read_b64_tr_b16 v[198:199], v250 offset:50240
	ds_read_b64_tr_b16 v[200:201], v250 offset:52800
	s_waitcnt lgkmcnt(8)
	v_mfma_f32_32x32x16_bf16 v[50:65], v[230:233], v[246:249], v[50:65]
	v_max3_f32 v252, v252, v75, v92
	v_max3_f32 v253, v253, v79, v96
	v_max3_f32 v0, v0, v68, v85
	s_waitcnt lgkmcnt(6)
	v_mfma_f32_32x32x16_bf16 v[34:49], v[218:221], v[234:237], v[34:49]
	v_max3_f32 v251, v251, v72, v89
	v_max3_f32 v252, v252, v76, v93
	v_max3_f32 v253, v253, v80, v97
	s_waitcnt lgkmcnt(4)
	v_mfma_f32_32x32x16_bf16 v[34:49], v[222:225], v[242:245], v[34:49]
	v_max_f32_e32 v0, v0, v69
	v_max_f32_e32 v251, v251, v73
	v_max_f32_e32 v252, v252, v77
	s_waitcnt lgkmcnt(2)
	v_mfma_f32_32x32x16_bf16 v[34:49], v[226:229], v[238:241], v[34:49]
	v_max_f32_e32 v253, v253, v81
	v_max3_f32 v0, v0, v251, v252
	v_max_f32_e32 v0, v0, v253
	ds_read_b64_tr_b16 v[218:219], v250 offset:34944
	ds_read_b64_tr_b16 v[220:221], v250 offset:37504
	ds_read_b64_tr_b16 v[222:223], v250 offset:40064
	ds_read_b64_tr_b16 v[224:225], v250 offset:42624
	ds_read_b64_tr_b16 v[226:227], v250 offset:45184
	ds_read_b64_tr_b16 v[228:229], v250 offset:47744
	ds_read_b64_tr_b16 v[230:231], v250 offset:50304
	ds_read_b64_tr_b16 v[232:233], v250 offset:52864
	s_waitcnt lgkmcnt(8)
	v_mfma_f32_32x32x16_bf16 v[34:49], v[198:201], v[246:249], v[34:49]
	s_nop 0
	v_mov_b32_e32 v251, v0
	v_nop
	s_waitcnt lgkmcnt(6)
	v_mfma_f32_32x32x16_bf16 v[18:33], v[218:221], v[234:237], v[18:33]
	v_nop
	v_permlane32_swap_b32 v0, v251
	s_nop 0
	s_waitcnt lgkmcnt(4)
	v_mfma_f32_32x32x16_bf16 v[18:33], v[222:225], v[242:245], v[18:33]
	v_max_f32_e32 v251, v251, v251
	v_max_f32_e32 v0, v0, v0
	v_max_f32_e32 v0, v0, v251
	s_waitcnt lgkmcnt(2)
	v_mfma_f32_32x32x16_bf16 v[18:33], v[226:229], v[238:241], v[18:33]
	v_add_f32_e32 v251, 0x42800000, v197
	v_cmp_gt_f32_e32 vcc, v0, v251
	ds_read_b64_tr_b16 v[218:219], v250 offset:35008
	ds_read_b64_tr_b16 v[220:221], v250 offset:37568
	ds_read_b64_tr_b16 v[222:223], v250 offset:40128
	ds_read_b64_tr_b16 v[224:225], v250 offset:42688
	ds_read_b64_tr_b16 v[226:227], v250 offset:45248
	ds_read_b64_tr_b16 v[228:229], v250 offset:47808
	ds_read_b64_tr_b16 v[198:199], v250 offset:50368
	ds_read_b64_tr_b16 v[200:201], v250 offset:52928
	s_waitcnt lgkmcnt(8)
	v_mfma_f32_32x32x16_bf16 v[18:33], v[230:233], v[246:249], v[18:33]
	s_waitcnt lgkmcnt(6)
	v_mfma_f32_32x32x16_bf16 v[2:17], v[218:221], v[234:237], v[2:17]
	s_waitcnt lgkmcnt(4)
	v_mfma_f32_32x32x16_bf16 v[2:17], v[222:225], v[242:245], v[2:17]
	s_waitcnt lgkmcnt(2)
	v_mfma_f32_32x32x16_bf16 v[2:17], v[226:229], v[238:241], v[2:17]
	s_waitcnt lgkmcnt(0)
	v_mfma_f32_32x32x16_bf16 v[2:17], v[198:201], v[246:249], v[2:17]
	s_branch .Lff1b_copy
.Lff1b_first:
	s_mul_i32 s34, s27, 0x4400
	v_add_u32_e32 v0, s34, v162
	ds_read_b128 v[198:201], v0
	ds_read_b128 v[202:205], v0 offset:32
	ds_read_b128 v[206:209], v0 offset:8704
	ds_read_b128 v[210:213], v0 offset:8736
	v_add_u32_e32 v78, s4, v149
	v_add_u32_e32 v66, 0x12800, v78
	v_add_u32_e32 v67, 0x12880, v78
	v_add_u32_e32 v70, 0x12820, v78
	v_add_u32_e32 v71, 0x128a0, v78
	v_add_u32_e32 v74, 0x12840, v78
	v_add_u32_e32 v75, 0x128c0, v78
	v_add_u32_e32 v79, 0x12860, v78
	v_add_u32_e32 v78, 0x128e0, v78
	ds_read_b128 v[82:85], v66
	ds_read_b128 v[66:69], v67
	ds_read_b128 v[86:89], v70
	ds_read_b128 v[70:73], v71
	ds_read_b128 v[90:93], v74
	ds_read_b128 v[74:77], v75
	ds_read_b128 v[94:97], v79
	ds_read_b128 v[78:81], v78
	s_waitcnt lgkmcnt(1)
	v_mfma_f32_32x32x16_bf16 v[82:97], v[198:201], v[98:101], v[82:97]
	s_waitcnt lgkmcnt(0)
	v_mfma_f32_32x32x16_bf16 v[66:81], v[206:209], v[98:101], v[66:81]
	v_mfma_f32_32x32x16_bf16 v[82:97], v[202:205], v[102:105], v[82:97]
	ds_read_b128 v[198:201], v0 offset:64
	ds_read_b128 v[202:205], v0 offset:96
	ds_read_b128 v[206:209], v0 offset:8768
	ds_read_b128 v[214:217], v0 offset:8800
	v_mfma_f32_32x32x16_bf16 v[66:81], v[210:213], v[102:105], v[66:81]
	s_waitcnt lgkmcnt(3)
	v_mfma_f32_32x32x16_bf16 v[82:97], v[198:201], v[106:109], v[82:97]
	s_waitcnt lgkmcnt(1)
	v_mfma_f32_32x32x16_bf16 v[66:81], v[206:209], v[106:109], v[66:81]
	v_mfma_f32_32x32x16_bf16 v[82:97], v[202:205], v[110:113], v[82:97]
	ds_read_b128 v[198:201], v0 offset:128
	ds_read_b128 v[202:205], v0 offset:160
	ds_read_b128 v[206:209], v0 offset:8832
	ds_read_b128 v[210:213], v0 offset:8864
	s_waitcnt lgkmcnt(4)
	v_mfma_f32_32x32x16_bf16 v[66:81], v[214:217], v[110:113], v[66:81]
	s_waitcnt lgkmcnt(3)
	v_mfma_f32_32x32x16_bf16 v[82:97], v[198:201], v[114:117], v[82:97]
	s_waitcnt lgkmcnt(1)
	v_mfma_f32_32x32x16_bf16 v[66:81], v[206:209], v[114:117], v[66:81]
	v_mfma_f32_32x32x16_bf16 v[82:97], v[202:205], v[118:121], v[82:97]
	ds_read_b128 v[198:201], v0 offset:192
	ds_read_b128 v[202:205], v0 offset:224
	ds_read_b128 v[206:209], v0 offset:8896
	ds_read_b128 v[214:217], v0 offset:8928
	s_waitcnt lgkmcnt(4)
	v_mfma_f32_32x32x16_bf16 v[66:81], v[210:213], v[118:121], v[66:81]
	s_waitcnt lgkmcnt(3)
	v_mfma_f32_32x32x16_bf16 v[82:97], v[198:201], v[122:125], v[82:97]
	s_waitcnt lgkmcnt(1)
	v_mfma_f32_32x32x16_bf16 v[66:81], v[206:209], v[122:125], v[66:81]
	v_mfma_f32_32x32x16_bf16 v[82:97], v[202:205], v[126:129], v[82:97]
	s_waitcnt lgkmcnt(0)
	v_mfma_f32_32x32x16_bf16 v[66:81], v[214:217], v[126:129], v[66:81]
	s_cmp_le_i32 s26, s5
	s_cbranch_scc1 .Lff1b_m1
	v_cmp_le_i32_e32 vcc, v165, v195
	s_nop 8
	v_cndmask_b32_e32 v66, v155, v66, vcc
	v_cmp_lt_i32_e32 vcc, v163, v195
	s_nop 1
	v_cndmask_b32_e32 v83, v155, v83, vcc
	v_cmp_le_i32_e32 vcc, v163, v195
	s_nop 1
	v_cndmask_b32_e32 v82, v155, v82, vcc
	v_cmp_le_i32_e32 vcc, v166, v195
	s_nop 1
	v_cndmask_b32_e32 v67, v155, v67, vcc
	v_cmp_le_i32_e32 vcc, v167, v195
	s_nop 1
	v_cndmask_b32_e32 v84, v155, v84, vcc
	v_cmp_le_i32_e32 vcc, v168, v195
	s_nop 1
	v_cndmask_b32_e32 v68, v155, v68, vcc
	v_cmp_le_i32_e32 vcc, v169, v195
	s_nop 1
	v_cndmask_b32_e32 v85, v155, v85, vcc
	v_cmp_le_i32_e32 vcc, v170, v195
	s_nop 1
	v_cndmask_b32_e32 v69, v155, v69, vcc
	v_cmp_le_i32_e32 vcc, v171, v195
	s_nop 1
	v_cndmask_b32_e32 v86, v155, v86, vcc
	v_cmp_le_i32_e32 vcc, v172, v195
	s_nop 1
	v_cndmask_b32_e32 v70, v155, v70, vcc
	v_cmp_le_i32_e32 vcc, v173, v195
	s_nop 1
	v_cndmask_b32_e32 v87, v155, v87, vcc
	v_cmp_le_i32_e32 vcc, v174, v195
	s_nop 1
	v_cndmask_b32_e32 v71, v155, v71, vcc
	v_cmp_le_i32_e32 vcc, v175, v195
	s_nop 1
	v_cndmask_b32_e32 v88, v155, v88, vcc
	v_cmp_le_i32_e32 vcc, v176, v195
	s_nop 1
	v_cndmask_b32_e32 v72, v155, v72, vcc
	v_cmp_le_i32_e32 vcc, v177, v195
	s_nop 1
	v_cndmask_b32_e32 v89, v155, v89, vcc
	v_cmp_le_i32_e32 vcc, v178, v195
	s_nop 1
	v_cndmask_b32_e32 v73, v155, v73, vcc
	v_cmp_le_i32_e32 vcc, v179, v195
	s_nop 1
	v_cndmask_b32_e32 v90, v155, v90, vcc
	v_cmp_le_i32_e32 vcc, v180, v195
	s_nop 1
	v_cndmask_b32_e32 v74, v155, v74, vcc
	v_cmp_le_i32_e32 vcc, v181, v195
	s_nop 1
	v_cndmask_b32_e32 v91, v155, v91, vcc
	v_cmp_le_i32_e32 vcc, v182, v195
	s_nop 1
	v_cndmask_b32_e32 v75, v155, v75, vcc
	v_cmp_le_i32_e32 vcc, v183, v195
	s_nop 1
	v_cndmask_b32_e32 v92, v155, v92, vcc
	v_cmp_le_i32_e32 vcc, v184, v195
	s_nop 1
	v_cndmask_b32_e32 v76, v155, v76, vcc
	v_cmp_le_i32_e32 vcc, v185, v195
	s_nop 1
	v_cndmask_b32_e32 v93, v155, v93, vcc
	v_cmp_le_i32_e32 vcc, v186, v195
	s_nop 1
	v_cndmask_b32_e32 v77, v155, v77, vcc
	v_cmp_le_i32_e32 vcc, v187, v195
	s_nop 1
	v_cndmask_b32_e32 v94, v155, v94, vcc
	v_cmp_le_i32_e32 vcc, v188, v195
	s_nop 1
	v_cndmask_b32_e32 v78, v155, v78, vcc
	v_cmp_le_i32_e32 vcc, v189, v195
	s_nop 1
	v_cndmask_b32_e32 v95, v155, v95, vcc
	v_cmp_le_i32_e32 vcc, v190, v195
	s_nop 1
	v_cndmask_b32_e32 v79, v155, v79, vcc
	v_cmp_le_i32_e32 vcc, v191, v195
	s_nop 1
	v_cndmask_b32_e32 v96, v155, v96, vcc
	v_cmp_le_i32_e32 vcc, v192, v195
	s_nop 1
	v_cndmask_b32_e32 v80, v155, v80, vcc
	v_cmp_le_i32_e32 vcc, v193, v195
	s_nop 1
	v_cndmask_b32_e32 v97, v155, v97, vcc
	v_cmp_le_i32_e32 vcc, v194, v195
	s_nop 1
	v_cndmask_b32_e32 v81, v155, v81, vcc
.Lff1b_m1:
	s_nop 11
	v_max3_f32 v0, v82, v66, v83
	v_max3_f32 v251, v86, v70, v87
	v_max3_f32 v252, v90, v74, v91
	v_max3_f32 v253, v94, v78, v95
	v_max3_f32 v0, v0, v67, v84
	v_max3_f32 v251, v251, v71, v88
	v_max3_f32 v252, v252, v75, v92
	v_max3_f32 v253, v253, v79, v96
	v_max3_f32 v0, v0, v68, v85
	v_max3_f32 v251, v251, v72, v89
	v_max3_f32 v252, v252, v76, v93
	v_max3_f32 v253, v253, v80, v97
	v_max_f32_e32 v0, v0, v69
	v_max_f32_e32 v251, v251, v73
	v_max_f32_e32 v252, v252, v77
	v_max_f32_e32 v253, v253, v81
	v_max3_f32 v0, v0, v251, v252
	v_max_f32_e32 v0, v0, v253
	s_nop 0
	v_mov_b32_e32 v251, v0
	v_nop
	v_nop
	v_permlane32_swap_b32 v0, v251
	s_nop 0
	v_max_f32_e32 v251, v251, v251
	v_max_f32_e32 v0, v0, v0
	v_max_f32_e32 v0, v0, v251
	v_add_f32_e32 v251, 0x42800000, v197
	v_cmp_gt_f32_e32 vcc, v0, v251

.Lff1b_inact:
	s_cmp_eq_u32 s72, 0
	s_cbranch_scc1 .Lff1b_bar
	v_sub_f32_e32 v218, v218, v197
	v_sub_f32_e32 v219, v219, v197
	v_sub_f32_e32 v220, v220, v197
	v_sub_f32_e32 v221, v221, v197
	v_exp_f32_e32 v218, v218
	v_exp_f32_e32 v219, v219
	v_exp_f32_e32 v220, v220
	v_exp_f32_e32 v221, v221
	v_sub_f32_e32 v222, v222, v197
	v_sub_f32_e32 v223, v223, v197
	v_sub_f32_e32 v224, v224, v197
	v_sub_f32_e32 v225, v225, v197
	v_exp_f32_e32 v222, v222
	v_exp_f32_e32 v223, v223
	v_exp_f32_e32 v224, v224
	v_exp_f32_e32 v225, v225
	v_sub_f32_e32 v234, v234, v197
	v_sub_f32_e32 v235, v235, v197
	v_sub_f32_e32 v236, v236, v197
	v_sub_f32_e32 v237, v237, v197
	v_exp_f32_e32 v234, v234
	v_exp_f32_e32 v235, v235
	v_exp_f32_e32 v236, v236
	v_exp_f32_e32 v237, v237
	v_add_f32_e32 v250, v218, v222
	v_add_f32_e32 v251, v219, v223
	v_add_f32_e32 v252, v220, v224
	v_add_f32_e32 v253, v221, v225
	v_sub_f32_e32 v238, v238, v197
	v_sub_f32_e32 v239, v239, v197
	v_sub_f32_e32 v240, v240, v197
	v_sub_f32_e32 v241, v241, v197
	v_exp_f32_e32 v238, v238
	v_exp_f32_e32 v239, v239
	v_exp_f32_e32 v240, v240
	v_exp_f32_e32 v241, v241
	v_add_f32_e32 v250, v250, v234
	v_add_f32_e32 v251, v251, v235
	v_add_f32_e32 v252, v252, v236
	v_add_f32_e32 v253, v253, v237
	v_sub_f32_e32 v226, v226, v197
	v_sub_f32_e32 v227, v227, v197
	v_sub_f32_e32 v228, v228, v197
	v_sub_f32_e32 v229, v229, v197
	v_exp_f32_e32 v226, v226
	v_exp_f32_e32 v227, v227
	v_exp_f32_e32 v228, v228
	v_exp_f32_e32 v229, v229
	v_add_f32_e32 v250, v250, v238
	v_add_f32_e32 v251, v251, v239
	v_add_f32_e32 v252, v252, v240
	v_add_f32_e32 v253, v253, v241
	v_sub_f32_e32 v230, v230, v197
	v_sub_f32_e32 v231, v231, v197
	v_sub_f32_e32 v232, v232, v197
	v_sub_f32_e32 v233, v233, v197
	v_exp_f32_e32 v230, v230
	v_exp_f32_e32 v231, v231
	v_exp_f32_e32 v232, v232
	v_exp_f32_e32 v233, v233
	v_add_f32_e32 v250, v250, v226
	v_add_f32_e32 v251, v251, v227
	v_add_f32_e32 v252, v252, v228
	v_add_f32_e32 v253, v253, v229
	v_sub_f32_e32 v242, v242, v197
	v_sub_f32_e32 v243, v243, v197
	v_sub_f32_e32 v244, v244, v197
	v_sub_f32_e32 v245, v245, v197
	v_exp_f32_e32 v242, v242
	v_exp_f32_e32 v243, v243
	v_exp_f32_e32 v244, v244
	v_exp_f32_e32 v245, v245
	v_add_f32_e32 v250, v250, v230
	v_add_f32_e32 v251, v251, v231
	v_add_f32_e32 v252, v252, v232
	v_add_f32_e32 v253, v253, v233
	v_sub_f32_e32 v246, v246, v197
	v_sub_f32_e32 v247, v247, v197
	v_sub_f32_e32 v248, v248, v197
	v_sub_f32_e32 v249, v249, v197
	v_exp_f32_e32 v246, v246
	v_exp_f32_e32 v247, v247
	v_exp_f32_e32 v248, v248
	v_exp_f32_e32 v249, v249
	v_add_f32_e32 v250, v250, v242
	v_add_f32_e32 v251, v251, v243
	v_add_f32_e32 v252, v252, v244
	v_add_f32_e32 v253, v253, v245
	v_add_f32_e32 v250, v250, v246
	v_add_f32_e32 v251, v251, v247
	v_add_f32_e32 v252, v252, v248
	v_add_f32_e32 v253, v253, v249
	v_add_f32_e32 v250, v250, v251
	v_add_f32_e32 v252, v252, v253
	v_add_f32_e32 v250, v250, v252
	v_add_f32_e32 v196, v196, v250
	v_cvt_pk_bf16_f32 v241, v240, v241
	v_cvt_pk_bf16_f32 v240, v238, v239
	v_cvt_pk_bf16_f32 v239, v236, v237
	v_cvt_pk_bf16_f32 v238, v234, v235
	v_cvt_pk_bf16_f32 v234, v218, v219
	v_cvt_pk_bf16_f32 v235, v220, v221
	v_cvt_pk_bf16_f32 v236, v222, v223
	v_cvt_pk_bf16_f32 v237, v224, v225
	v_cvt_pk_bf16_f32 v249, v248, v249
	v_cvt_pk_bf16_f32 v248, v246, v247
	v_cvt_pk_bf16_f32 v247, v244, v245
	v_cvt_pk_bf16_f32 v246, v242, v243
	v_cvt_pk_bf16_f32 v242, v226, v227
	v_cvt_pk_bf16_f32 v243, v228, v229
	v_cvt_pk_bf16_f32 v244, v230, v231
	v_cvt_pk_bf16_f32 v245, v232, v233
	v_add_u32_e32 v250, s70, v164
	ds_read_b64_tr_b16 v[218:219], v250 offset:34816
	ds_read_b64_tr_b16 v[220:221], v250 offset:37376
	ds_read_b64_tr_b16 v[222:223], v250 offset:39936
	ds_read_b64_tr_b16 v[224:225], v250 offset:42496
	ds_read_b64_tr_b16 v[226:227], v250 offset:45056
	ds_read_b64_tr_b16 v[228:229], v250 offset:47616
	ds_read_b64_tr_b16 v[230:231], v250 offset:50176
	ds_read_b64_tr_b16 v[232:233], v250 offset:52736
	s_waitcnt lgkmcnt(6)
	v_mfma_f32_32x32x16_bf16 v[50:65], v[218:221], v[234:237], v[50:65]
	s_waitcnt lgkmcnt(4)
	v_mfma_f32_32x32x16_bf16 v[50:65], v[222:225], v[242:245], v[50:65]
	s_waitcnt lgkmcnt(2)
	v_mfma_f32_32x32x16_bf16 v[50:65], v[226:229], v[238:241], v[50:65]
	ds_read_b64_tr_b16 v[218:219], v250 offset:34880
	ds_read_b64_tr_b16 v[220:221], v250 offset:37440
	ds_read_b64_tr_b16 v[222:223], v250 offset:40000
	ds_read_b64_tr_b16 v[224:225], v250 offset:42560
	ds_read_b64_tr_b16 v[226:227], v250 offset:45120
	ds_read_b64_tr_b16 v[228:229], v250 offset:47680
	ds_read_b64_tr_b16 v[198:199], v250 offset:50240
	ds_read_b64_tr_b16 v[200:201], v250 offset:52800
	s_waitcnt lgkmcnt(8)
	v_mfma_f32_32x32x16_bf16 v[50:65], v[230:233], v[246:249], v[50:65]
	s_waitcnt lgkmcnt(6)
	v_mfma_f32_32x32x16_bf16 v[34:49], v[218:221], v[234:237], v[34:49]
	s_waitcnt lgkmcnt(4)
	v_mfma_f32_32x32x16_bf16 v[34:49], v[222:225], v[242:245], v[34:49]
	s_waitcnt lgkmcnt(2)
	v_mfma_f32_32x32x16_bf16 v[34:49], v[226:229], v[238:241], v[34:49]
	ds_read_b64_tr_b16 v[218:219], v250 offset:34944
	ds_read_b64_tr_b16 v[220:221], v250 offset:37504
	ds_read_b64_tr_b16 v[222:223], v250 offset:40064
	ds_read_b64_tr_b16 v[224:225], v250 offset:42624
	ds_read_b64_tr_b16 v[226:227], v250 offset:45184
	ds_read_b64_tr_b16 v[228:229], v250 offset:47744
	ds_read_b64_tr_b16 v[230:231], v250 offset:50304
	ds_read_b64_tr_b16 v[232:233], v250 offset:52864
	s_waitcnt lgkmcnt(8)
	v_mfma_f32_32x32x16_bf16 v[34:49], v[198:201], v[246:249], v[34:49]
	s_waitcnt lgkmcnt(6)
	v_mfma_f32_32x32x16_bf16 v[18:33], v[218:221], v[234:237], v[18:33]
	s_waitcnt lgkmcnt(4)
	v_mfma_f32_32x32x16_bf16 v[18:33], v[222:225], v[242:245], v[18:33]
	s_waitcnt lgkmcnt(2)
	v_mfma_f32_32x32x16_bf16 v[18:33], v[226:229], v[238:241], v[18:33]
	ds_read_b64_tr_b16 v[218:219], v250 offset:35008
	ds_read_b64_tr_b16 v[220:221], v250 offset:37568
	ds_read_b64_tr_b16 v[222:223], v250 offset:40128
	ds_read_b64_tr_b16 v[224:225], v250 offset:42688
	ds_read_b64_tr_b16 v[226:227], v250 offset:45248
	ds_read_b64_tr_b16 v[228:229], v250 offset:47808
	ds_read_b64_tr_b16 v[198:199], v250 offset:50368
	ds_read_b64_tr_b16 v[200:201], v250 offset:52928
	s_waitcnt lgkmcnt(8)
	v_mfma_f32_32x32x16_bf16 v[18:33], v[230:233], v[246:249], v[18:33]
	s_waitcnt lgkmcnt(6)
	v_mfma_f32_32x32x16_bf16 v[2:17], v[218:221], v[234:237], v[2:17]
	s_waitcnt lgkmcnt(4)
	v_mfma_f32_32x32x16_bf16 v[2:17], v[222:225], v[242:245], v[2:17]
	s_waitcnt lgkmcnt(2)
	v_mfma_f32_32x32x16_bf16 v[2:17], v[226:229], v[238:241], v[2:17]
	s_waitcnt lgkmcnt(0)
	v_mfma_f32_32x32x16_bf16 v[2:17], v[198:201], v[246:249], v[2:17]
	s_mov_b32 s72, 0

.Lff2b_top:
	s_add_i32 s7, s25, -2
	s_and_b32 s7, s7, 1
	s_xor_b32 s20, s7, 1
	s_mul_i32 s21, s20, 0x4400
	s_add_i32 s21, s21, 0
	s_mulk_i32 s20, 0xc00
	s_add_i32 s20, s21, s20
	v_add3_u32 v0, s21, v149, v156
	s_waitcnt vmcnt(3)
	ds_write_b128 v0, v[130:133]
	v_add3_u32 v0, s68, v157, v156
	s_waitcnt vmcnt(2)
	ds_write_b128 v0, v[134:137] offset:34816
	v_add3_u32 v0, s21, v158, v159
	s_cmp_lt_u32 s25, s23
	s_waitcnt vmcnt(1)
	ds_write_b128 v0, v[138:141]
	v_add3_u32 v0, s68, v160, v159
	s_cselect_b32 s20, s25, s33
	s_lshl_b32 s20, s20, 6
	v_add_u32_e32 v250, s20, v146
	v_ashrrev_i32_e32 v251, 31, v250
	v_lshlrev_b64 v[250:251], 14, v[250:251]
	v_lshl_add_u64 v[250:251], v[150:151], 0, v[250:251]
	v_add_co_u32_e32 v252, vcc, s42, v250
	s_waitcnt vmcnt(0)
	ds_write_b128 v0, v[142:145] offset:34816
	v_addc_co_u32_e32 v253, vcc, 0, v251, vcc
	v_add_co_u32_e32 v250, vcc, 0x2000, v250
	s_nop 1
	v_addc_co_u32_e32 v251, vcc, 0, v251, vcc
	global_load_dwordx4 v[130:133], v[252:253], off
	global_load_dwordx4 v[134:137], v[250:251], off
	v_add_u32_e32 v250, s20, v148
	v_ashrrev_i32_e32 v251, 31, v250
	v_lshlrev_b64 v[250:251], 14, v[250:251]
	v_lshl_add_u64 v[250:251], v[152:153], 0, v[250:251]
	v_add_co_u32_e32 v252, vcc, 0x1000, v250
	s_sub_i32 s20, s26, 63
	s_nop 0
	v_addc_co_u32_e32 v253, vcc, 0, v251, vcc
	v_add_co_u32_e32 v250, vcc, 0x2000, v250
	s_cmp_gt_i32 s20, s27
	s_nop 0
	v_addc_co_u32_e32 v251, vcc, 0, v251, vcc
	global_load_dwordx4 v[138:141], v[252:253], off
	global_load_dwordx4 v[142:145], v[250:251], off
	s_sub_i32 s20, s26, 63
	s_cmp_gt_i32 s20, s27
	s_cbranch_scc1 .Lff2b_inact
	s_cmp_eq_u32 s72, 0
	s_cbranch_scc1 .Lff2b_first
	s_mul_i32 s20, s7, 0x4400
	v_add_u32_e32 v0, s20, v162
	ds_read_b128 v[198:201], v0
	ds_read_b128 v[202:205], v0 offset:32
	ds_read_b128 v[206:209], v0 offset:8704
	ds_read_b128 v[210:213], v0 offset:8736
	v_add_u32_e32 v78, s24, v161
	v_add_u32_e32 v66, 0x12800, v78
	v_add_u32_e32 v67, 0x12880, v78
	v_add_u32_e32 v70, 0x12820, v78
	v_add_u32_e32 v71, 0x128a0, v78
	v_add_u32_e32 v74, 0x12840, v78
	v_add_u32_e32 v75, 0x128c0, v78
	v_add_u32_e32 v79, 0x12860, v78
	v_add_u32_e32 v78, 0x128e0, v78
	ds_read_b128 v[82:85], v66
	ds_read_b128 v[66:69], v67
	ds_read_b128 v[86:89], v70
	ds_read_b128 v[70:73], v71
	ds_read_b128 v[90:93], v74
	ds_read_b128 v[74:77], v75
	ds_read_b128 v[94:97], v79
	ds_read_b128 v[78:81], v78
	s_waitcnt lgkmcnt(1)
	v_mfma_f32_32x32x16_bf16 v[82:97], v[198:201], v[98:101], v[82:97]
	v_sub_f32_e32 v218, v218, v197
	v_sub_f32_e32 v219, v219, v197
	v_sub_f32_e32 v220, v220, v197
	v_sub_f32_e32 v221, v221, v197
	v_exp_f32_e32 v218, v218
	v_exp_f32_e32 v219, v219
	v_exp_f32_e32 v220, v220
	v_exp_f32_e32 v221, v221
	s_waitcnt lgkmcnt(0)
	v_mfma_f32_32x32x16_bf16 v[66:81], v[206:209], v[98:101], v[66:81]
	v_sub_f32_e32 v222, v222, v197
	v_sub_f32_e32 v223, v223, v197
	v_sub_f32_e32 v224, v224, v197
	v_sub_f32_e32 v225, v225, v197
	v_exp_f32_e32 v222, v222
	v_exp_f32_e32 v223, v223
	v_exp_f32_e32 v224, v224
	v_exp_f32_e32 v225, v225
	v_mfma_f32_32x32x16_bf16 v[82:97], v[202:205], v[102:105], v[82:97]
	v_sub_f32_e32 v234, v234, v197
	v_sub_f32_e32 v235, v235, v197
	v_sub_f32_e32 v236, v236, v197
	v_sub_f32_e32 v237, v237, v197
	v_exp_f32_e32 v234, v234
	v_exp_f32_e32 v235, v235
	v_exp_f32_e32 v236, v236
	v_exp_f32_e32 v237, v237
	ds_read_b128 v[198:201], v0 offset:64
	ds_read_b128 v[202:205], v0 offset:96
	ds_read_b128 v[206:209], v0 offset:8768
	ds_read_b128 v[214:217], v0 offset:8800
	v_mfma_f32_32x32x16_bf16 v[66:81], v[210:213], v[102:105], v[66:81]
	v_add_f32_e32 v250, v218, v222
	v_add_f32_e32 v251, v219, v223
	v_add_f32_e32 v252, v220, v224
	v_add_f32_e32 v253, v221, v225
	v_sub_f32_e32 v238, v238, v197
	v_sub_f32_e32 v239, v239, v197
	v_sub_f32_e32 v240, v240, v197
	v_sub_f32_e32 v241, v241, v197
	s_waitcnt lgkmcnt(3)
	v_mfma_f32_32x32x16_bf16 v[82:97], v[198:201], v[106:109], v[82:97]
	v_exp_f32_e32 v238, v238
	v_exp_f32_e32 v239, v239
	v_exp_f32_e32 v240, v240
	v_exp_f32_e32 v241, v241
	v_add_f32_e32 v250, v250, v234
	v_add_f32_e32 v251, v251, v235
	v_add_f32_e32 v252, v252, v236
	v_add_f32_e32 v253, v253, v237
	s_waitcnt lgkmcnt(1)
	v_mfma_f32_32x32x16_bf16 v[66:81], v[206:209], v[106:109], v[66:81]
	v_sub_f32_e32 v226, v226, v197
	v_sub_f32_e32 v227, v227, v197
	v_sub_f32_e32 v228, v228, v197
	v_sub_f32_e32 v229, v229, v197
	v_exp_f32_e32 v226, v226
	v_exp_f32_e32 v227, v227
	v_exp_f32_e32 v228, v228
	v_exp_f32_e32 v229, v229
	v_mfma_f32_32x32x16_bf16 v[82:97], v[202:205], v[110:113], v[82:97]
	v_add_f32_e32 v250, v250, v238
	v_add_f32_e32 v251, v251, v239
	v_add_f32_e32 v252, v252, v240
	v_add_f32_e32 v253, v253, v241
	v_sub_f32_e32 v230, v230, v197
	v_sub_f32_e32 v231, v231, v197
	v_sub_f32_e32 v232, v232, v197
	v_sub_f32_e32 v233, v233, v197
	ds_read_b128 v[198:201], v0 offset:128
	ds_read_b128 v[202:205], v0 offset:160
	ds_read_b128 v[206:209], v0 offset:8832
	ds_read_b128 v[210:213], v0 offset:8864
	s_waitcnt lgkmcnt(4)
	v_mfma_f32_32x32x16_bf16 v[66:81], v[214:217], v[110:113], v[66:81]
	v_exp_f32_e32 v230, v230
	v_exp_f32_e32 v231, v231
	v_exp_f32_e32 v232, v232
	v_exp_f32_e32 v233, v233
	v_add_f32_e32 v250, v250, v226
	v_add_f32_e32 v251, v251, v227
	v_add_f32_e32 v252, v252, v228
	v_add_f32_e32 v253, v253, v229
	s_waitcnt lgkmcnt(3)
	v_mfma_f32_32x32x16_bf16 v[82:97], v[198:201], v[114:117], v[82:97]
	v_sub_f32_e32 v242, v242, v197
	v_sub_f32_e32 v243, v243, v197
	v_sub_f32_e32 v244, v244, v197
	v_sub_f32_e32 v245, v245, v197
	v_exp_f32_e32 v242, v242
	v_exp_f32_e32 v243, v243
	v_exp_f32_e32 v244, v244
	v_exp_f32_e32 v245, v245
	s_waitcnt lgkmcnt(1)
	v_mfma_f32_32x32x16_bf16 v[66:81], v[206:209], v[114:117], v[66:81]
	v_add_f32_e32 v250, v250, v230
	v_add_f32_e32 v251, v251, v231
	v_add_f32_e32 v252, v252, v232
	v_add_f32_e32 v253, v253, v233
	v_sub_f32_e32 v246, v246, v197
	v_sub_f32_e32 v247, v247, v197
	v_sub_f32_e32 v248, v248, v197
	v_sub_f32_e32 v249, v249, v197
	v_mfma_f32_32x32x16_bf16 v[82:97], v[202:205], v[118:121], v[82:97]
	v_exp_f32_e32 v246, v246
	v_exp_f32_e32 v247, v247
	v_exp_f32_e32 v248, v248
	v_exp_f32_e32 v249, v249
	v_add_f32_e32 v250, v250, v242
	v_add_f32_e32 v251, v251, v243
	v_add_f32_e32 v252, v252, v244
	v_add_f32_e32 v253, v253, v245
	ds_read_b128 v[198:201], v0 offset:192
	ds_read_b128 v[202:205], v0 offset:224
	ds_read_b128 v[206:209], v0 offset:8896
	ds_read_b128 v[214:217], v0 offset:8928
	s_waitcnt lgkmcnt(4)
	v_mfma_f32_32x32x16_bf16 v[66:81], v[210:213], v[118:121], v[66:81]
	v_add_f32_e32 v250, v250, v246
	v_add_f32_e32 v251, v251, v247
	v_add_f32_e32 v252, v252, v248
	v_add_f32_e32 v253, v253, v249
	v_add_f32_e32 v250, v250, v251
	v_add_f32_e32 v252, v252, v253
	v_add_f32_e32 v250, v250, v252
	v_add_f32_e32 v196, v196, v250
	s_waitcnt lgkmcnt(3)
	v_mfma_f32_32x32x16_bf16 v[82:97], v[198:201], v[122:125], v[82:97]
	v_cvt_pk_bf16_f32 v241, v240, v241
	v_cvt_pk_bf16_f32 v240, v238, v239
	v_cvt_pk_bf16_f32 v239, v236, v237
	v_cvt_pk_bf16_f32 v238, v234, v235
	v_cvt_pk_bf16_f32 v234, v218, v219
	v_cvt_pk_bf16_f32 v235, v220, v221
	v_cvt_pk_bf16_f32 v236, v222, v223
	v_cvt_pk_bf16_f32 v237, v224, v225
	s_waitcnt lgkmcnt(1)
	v_mfma_f32_32x32x16_bf16 v[66:81], v[206:209], v[122:125], v[66:81]
	v_cvt_pk_bf16_f32 v249, v248, v249
	v_cvt_pk_bf16_f32 v248, v246, v247
	v_cvt_pk_bf16_f32 v247, v244, v245
	v_cvt_pk_bf16_f32 v246, v242, v243
	v_cvt_pk_bf16_f32 v242, v226, v227
	v_cvt_pk_bf16_f32 v243, v228, v229
	v_cvt_pk_bf16_f32 v244, v230, v231
	v_cvt_pk_bf16_f32 v245, v232, v233
	v_mfma_f32_32x32x16_bf16 v[82:97], v[202:205], v[126:129], v[82:97]
	s_waitcnt lgkmcnt(0)
	v_mfma_f32_32x32x16_bf16 v[66:81], v[214:217], v[126:129], v[66:81]
	s_cmp_le_i32 s26, s27
	s_cbranch_scc1 .Lff2b_z2
	v_cmp_le_i32_e32 vcc, v165, v195
	s_nop 8
	v_cndmask_b32_e32 v66, v155, v66, vcc
	v_cmp_lt_i32_e32 vcc, v163, v195
	s_nop 1
	v_cndmask_b32_e32 v83, v155, v83, vcc
	v_cmp_le_i32_e32 vcc, v163, v195
	s_nop 1
	v_cndmask_b32_e32 v82, v155, v82, vcc
	v_cmp_le_i32_e32 vcc, v166, v195
	s_nop 1
	v_cndmask_b32_e32 v67, v155, v67, vcc
	v_cmp_le_i32_e32 vcc, v167, v195
	s_nop 1
	v_cndmask_b32_e32 v84, v155, v84, vcc
	v_cmp_le_i32_e32 vcc, v168, v195
	s_nop 1
	v_cndmask_b32_e32 v68, v155, v68, vcc
	v_cmp_le_i32_e32 vcc, v169, v195
	s_nop 1
	v_cndmask_b32_e32 v85, v155, v85, vcc
	v_cmp_le_i32_e32 vcc, v170, v195
	s_nop 1
	v_cndmask_b32_e32 v69, v155, v69, vcc
	v_cmp_le_i32_e32 vcc, v171, v195
	s_nop 1
	v_cndmask_b32_e32 v86, v155, v86, vcc
	v_cmp_le_i32_e32 vcc, v172, v195
	s_nop 1
	v_cndmask_b32_e32 v70, v155, v70, vcc
	v_cmp_le_i32_e32 vcc, v173, v195
	s_nop 1
	v_cndmask_b32_e32 v87, v155, v87, vcc
	v_cmp_le_i32_e32 vcc, v174, v195
	s_nop 1
	v_cndmask_b32_e32 v71, v155, v71, vcc
	v_cmp_le_i32_e32 vcc, v175, v195
	s_nop 1
	v_cndmask_b32_e32 v88, v155, v88, vcc
	v_cmp_le_i32_e32 vcc, v176, v195
	s_nop 1
	v_cndmask_b32_e32 v72, v155, v72, vcc
	v_cmp_le_i32_e32 vcc, v177, v195
	s_nop 1
	v_cndmask_b32_e32 v89, v155, v89, vcc
	v_cmp_le_i32_e32 vcc, v178, v195
	s_nop 1
	v_cndmask_b32_e32 v73, v155, v73, vcc
	v_cmp_le_i32_e32 vcc, v179, v195
	s_nop 1
	v_cndmask_b32_e32 v90, v155, v90, vcc
	v_cmp_le_i32_e32 vcc, v180, v195
	s_nop 1
	v_cndmask_b32_e32 v74, v155, v74, vcc
	v_cmp_le_i32_e32 vcc, v181, v195
	s_nop 1
	v_cndmask_b32_e32 v91, v155, v91, vcc
	v_cmp_le_i32_e32 vcc, v182, v195
	s_nop 1
	v_cndmask_b32_e32 v75, v155, v75, vcc
	v_cmp_le_i32_e32 vcc, v183, v195
	s_nop 1
	v_cndmask_b32_e32 v92, v155, v92, vcc
	v_cmp_le_i32_e32 vcc, v184, v195
	s_nop 1
	v_cndmask_b32_e32 v76, v155, v76, vcc
	v_cmp_le_i32_e32 vcc, v185, v195
	s_nop 1
	v_cndmask_b32_e32 v93, v155, v93, vcc
	v_cmp_le_i32_e32 vcc, v186, v195
	s_nop 1
	v_cndmask_b32_e32 v77, v155, v77, vcc
	v_cmp_le_i32_e32 vcc, v187, v195
	s_nop 1
	v_cndmask_b32_e32 v94, v155, v94, vcc
	v_cmp_le_i32_e32 vcc, v188, v195
	s_nop 1
	v_cndmask_b32_e32 v78, v155, v78, vcc
	v_cmp_le_i32_e32 vcc, v189, v195
	s_nop 1
	v_cndmask_b32_e32 v95, v155, v95, vcc
	v_cmp_le_i32_e32 vcc, v190, v195
	s_nop 1
	v_cndmask_b32_e32 v79, v155, v79, vcc
	v_cmp_le_i32_e32 vcc, v191, v195
	s_nop 1
	v_cndmask_b32_e32 v96, v155, v96, vcc
	v_cmp_le_i32_e32 vcc, v192, v195
	s_nop 1
	v_cndmask_b32_e32 v80, v155, v80, vcc
	v_cmp_le_i32_e32 vcc, v193, v195
	s_nop 1
	v_cndmask_b32_e32 v97, v155, v97, vcc
	v_cmp_le_i32_e32 vcc, v194, v195
	s_nop 1
	v_cndmask_b32_e32 v81, v155, v81, vcc

.Lff2b_first:
	s_mul_i32 s20, s7, 0x4400
	v_add_u32_e32 v0, s20, v162
	ds_read_b128 v[198:201], v0
	ds_read_b128 v[202:205], v0 offset:32
	ds_read_b128 v[206:209], v0 offset:8704
	ds_read_b128 v[210:213], v0 offset:8736
	v_add_u32_e32 v78, s24, v161
	v_add_u32_e32 v66, 0x12800, v78
	v_add_u32_e32 v67, 0x12880, v78
	v_add_u32_e32 v70, 0x12820, v78
	v_add_u32_e32 v71, 0x128a0, v78
	v_add_u32_e32 v74, 0x12840, v78
	v_add_u32_e32 v75, 0x128c0, v78
	v_add_u32_e32 v79, 0x12860, v78
	v_add_u32_e32 v78, 0x128e0, v78
	ds_read_b128 v[82:85], v66
	ds_read_b128 v[66:69], v67
	ds_read_b128 v[86:89], v70
	ds_read_b128 v[70:73], v71
	ds_read_b128 v[90:93], v74
	ds_read_b128 v[74:77], v75
	ds_read_b128 v[94:97], v79
	ds_read_b128 v[78:81], v78
	s_waitcnt lgkmcnt(1)
	v_mfma_f32_32x32x16_bf16 v[82:97], v[198:201], v[98:101], v[82:97]
	s_waitcnt lgkmcnt(0)
	v_mfma_f32_32x32x16_bf16 v[66:81], v[206:209], v[98:101], v[66:81]
	v_mfma_f32_32x32x16_bf16 v[82:97], v[202:205], v[102:105], v[82:97]
	ds_read_b128 v[198:201], v0 offset:64
	ds_read_b128 v[202:205], v0 offset:96
	ds_read_b128 v[206:209], v0 offset:8768
	ds_read_b128 v[214:217], v0 offset:8800
	v_mfma_f32_32x32x16_bf16 v[66:81], v[210:213], v[102:105], v[66:81]
	s_waitcnt lgkmcnt(3)
	v_mfma_f32_32x32x16_bf16 v[82:97], v[198:201], v[106:109], v[82:97]
	s_waitcnt lgkmcnt(1)
	v_mfma_f32_32x32x16_bf16 v[66:81], v[206:209], v[106:109], v[66:81]
	v_mfma_f32_32x32x16_bf16 v[82:97], v[202:205], v[110:113], v[82:97]
	ds_read_b128 v[198:201], v0 offset:128
	ds_read_b128 v[202:205], v0 offset:160
	ds_read_b128 v[206:209], v0 offset:8832
	ds_read_b128 v[210:213], v0 offset:8864
	s_waitcnt lgkmcnt(4)
	v_mfma_f32_32x32x16_bf16 v[66:81], v[214:217], v[110:113], v[66:81]
	s_waitcnt lgkmcnt(3)
	v_mfma_f32_32x32x16_bf16 v[82:97], v[198:201], v[114:117], v[82:97]
	s_waitcnt lgkmcnt(1)
	v_mfma_f32_32x32x16_bf16 v[66:81], v[206:209], v[114:117], v[66:81]
	v_mfma_f32_32x32x16_bf16 v[82:97], v[202:205], v[118:121], v[82:97]
	ds_read_b128 v[198:201], v0 offset:192
	ds_read_b128 v[202:205], v0 offset:224
	ds_read_b128 v[206:209], v0 offset:8896
	ds_read_b128 v[214:217], v0 offset:8928
	s_waitcnt lgkmcnt(4)
	v_mfma_f32_32x32x16_bf16 v[66:81], v[210:213], v[118:121], v[66:81]
	s_waitcnt lgkmcnt(3)
	v_mfma_f32_32x32x16_bf16 v[82:97], v[198:201], v[122:125], v[82:97]
	s_waitcnt lgkmcnt(1)
	v_mfma_f32_32x32x16_bf16 v[66:81], v[206:209], v[122:125], v[66:81]
	v_mfma_f32_32x32x16_bf16 v[82:97], v[202:205], v[126:129], v[82:97]
	s_waitcnt lgkmcnt(0)
	v_mfma_f32_32x32x16_bf16 v[66:81], v[214:217], v[126:129], v[66:81]
	s_cmp_le_i32 s26, s27
	s_cbranch_scc1 .Lff2b_m1
	v_cmp_le_i32_e32 vcc, v165, v195
	s_nop 8
	v_cndmask_b32_e32 v66, v155, v66, vcc
	v_cmp_lt_i32_e32 vcc, v163, v195
	s_nop 1
	v_cndmask_b32_e32 v83, v155, v83, vcc
	v_cmp_le_i32_e32 vcc, v163, v195
	s_nop 1
	v_cndmask_b32_e32 v82, v155, v82, vcc
	v_cmp_le_i32_e32 vcc, v166, v195
	s_nop 1
	v_cndmask_b32_e32 v67, v155, v67, vcc
	v_cmp_le_i32_e32 vcc, v167, v195
	s_nop 1
	v_cndmask_b32_e32 v84, v155, v84, vcc
	v_cmp_le_i32_e32 vcc, v168, v195
	s_nop 1
	v_cndmask_b32_e32 v68, v155, v68, vcc
	v_cmp_le_i32_e32 vcc, v169, v195
	s_nop 1
	v_cndmask_b32_e32 v85, v155, v85, vcc
	v_cmp_le_i32_e32 vcc, v170, v195
	s_nop 1
	v_cndmask_b32_e32 v69, v155, v69, vcc
	v_cmp_le_i32_e32 vcc, v171, v195
	s_nop 1
	v_cndmask_b32_e32 v86, v155, v86, vcc
	v_cmp_le_i32_e32 vcc, v172, v195
	s_nop 1
	v_cndmask_b32_e32 v70, v155, v70, vcc
	v_cmp_le_i32_e32 vcc, v173, v195
	s_nop 1
	v_cndmask_b32_e32 v87, v155, v87, vcc
	v_cmp_le_i32_e32 vcc, v174, v195
	s_nop 1
	v_cndmask_b32_e32 v71, v155, v71, vcc
	v_cmp_le_i32_e32 vcc, v175, v195
	s_nop 1
	v_cndmask_b32_e32 v88, v155, v88, vcc
	v_cmp_le_i32_e32 vcc, v176, v195
	s_nop 1
	v_cndmask_b32_e32 v72, v155, v72, vcc
	v_cmp_le_i32_e32 vcc, v177, v195
	s_nop 1
	v_cndmask_b32_e32 v89, v155, v89, vcc
	v_cmp_le_i32_e32 vcc, v178, v195
	s_nop 1
	v_cndmask_b32_e32 v73, v155, v73, vcc
	v_cmp_le_i32_e32 vcc, v179, v195
	s_nop 1
	v_cndmask_b32_e32 v90, v155, v90, vcc
	v_cmp_le_i32_e32 vcc, v180, v195
	s_nop 1
	v_cndmask_b32_e32 v74, v155, v74, vcc
	v_cmp_le_i32_e32 vcc, v181, v195
	s_nop 1
	v_cndmask_b32_e32 v91, v155, v91, vcc
	v_cmp_le_i32_e32 vcc, v182, v195
	s_nop 1
	v_cndmask_b32_e32 v75, v155, v75, vcc
	v_cmp_le_i32_e32 vcc, v183, v195
	s_nop 1
	v_cndmask_b32_e32 v92, v155, v92, vcc
	v_cmp_le_i32_e32 vcc, v184, v195
	s_nop 1
	v_cndmask_b32_e32 v76, v155, v76, vcc
	v_cmp_le_i32_e32 vcc, v185, v195
	s_nop 1
	v_cndmask_b32_e32 v93, v155, v93, vcc
	v_cmp_le_i32_e32 vcc, v186, v195
	s_nop 1
	v_cndmask_b32_e32 v77, v155, v77, vcc
	v_cmp_le_i32_e32 vcc, v187, v195
	s_nop 1
	v_cndmask_b32_e32 v94, v155, v94, vcc
	v_cmp_le_i32_e32 vcc, v188, v195
	s_nop 1
	v_cndmask_b32_e32 v78, v155, v78, vcc
	v_cmp_le_i32_e32 vcc, v189, v195
	s_nop 1
	v_cndmask_b32_e32 v95, v155, v95, vcc
	v_cmp_le_i32_e32 vcc, v190, v195
	s_nop 1
	v_cndmask_b32_e32 v79, v155, v79, vcc
	v_cmp_le_i32_e32 vcc, v191, v195
	s_nop 1
	v_cndmask_b32_e32 v96, v155, v96, vcc
	v_cmp_le_i32_e32 vcc, v192, v195
	s_nop 1
	v_cndmask_b32_e32 v80, v155, v80, vcc
	v_cmp_le_i32_e32 vcc, v193, v195
	s_nop 1
	v_cndmask_b32_e32 v97, v155, v97, vcc
	v_cmp_le_i32_e32 vcc, v194, v195
	s_nop 1
	v_cndmask_b32_e32 v81, v155, v81, vcc
